# v33 + loop-edge edit: next-iteration slot offsets / prefetch mask computed in the PV s_nop pad instead of the iteration head (both wave halves)
# speedup vs baseline: 1.0086x; 1.0039x over previous
.LBB0_1598:
	s_lshl_b32 s65, s4, 1
	s_lshl_b32 s3, s5, 10
	s_lshr_b32 s59, s59, 6
	s_ashr_i32 s5, s3, 31
	s_add_i32 s66, s3, 0
	s_add_i32 s67, s65, 2
	s_add_u32 s4, s88, s3
	s_nop 1
	v_exp_f32_e32 v170, v2
	s_nop 0
	v_exp_f32_e32 v171, v18
	v_exp_f32_e32 v172, v3
	v_exp_f32_e32 v173, v19
	v_exp_f32_e32 v174, v4
	v_exp_f32_e32 v175, v20
	v_exp_f32_e32 v176, v5
	v_exp_f32_e32 v177, v21
	v_exp_f32_e32 v178, v6
	v_exp_f32_e32 v179, v22
	v_exp_f32_e32 v180, v7
	v_exp_f32_e32 v181, v23
	v_exp_f32_e32 v182, v8
	v_exp_f32_e32 v183, v24
	v_exp_f32_e32 v184, v9
	v_exp_f32_e32 v185, v25
	v_exp_f32_e32 v186, v10
	v_exp_f32_e32 v187, v26
	v_exp_f32_e32 v188, v11
	v_exp_f32_e32 v189, v27
	v_exp_f32_e32 v190, v12
	v_exp_f32_e32 v191, v28
	v_exp_f32_e32 v192, v13
	v_exp_f32_e32 v193, v29
	v_exp_f32_e32 v194, v14
	v_exp_f32_e32 v195, v30
	v_exp_f32_e32 v196, v15
	v_exp_f32_e32 v197, v31
	v_exp_f32_e32 v198, v16
	v_exp_f32_e32 v199, v32
	v_exp_f32_e32 v200, v17
	v_exp_f32_e32 v201, v33
	v_lshlrev_b32_e32 v2, 11, v165
	s_addc_u32 s5, s89, s5
	v_add3_u32 v209, 0, v2, v34
	v_lshlrev_b32_e32 v2, 4, v207
	v_mov_b32_e32 v3, v1
	v_lshl_add_u64 v[4:5], s[4:5], 0, v[0:1]
	v_mov_b32_e32 v14, v1
	v_mov_b32_e32 v15, v1
	v_lshl_add_u64 v[168:169], v[4:5], 0, v[2:3]
	v_mov_b32_e32 v0, v1
	v_mov_b32_e32 v2, v1
	v_mov_b32_e32 v4, v1
	v_mov_b32_e32 v5, v1
	v_mov_b32_e32 v6, v1
	v_mov_b32_e32 v7, v1
	v_mov_b32_e32 v8, v1
	v_mov_b32_e32 v9, v1
	v_mov_b32_e32 v10, v1
	v_mov_b32_e32 v11, v1
	v_mov_b32_e32 v12, v1
	v_mov_b32_e32 v13, v1
	v_mov_b64_e32 v[30:31], v[14:15]
	v_mov_b64_e32 v[46:47], v[14:15]
	v_mov_b64_e32 v[62:63], v[14:15]
	v_mov_b64_e32 v[78:79], v[14:15]
	s_mov_b32 s68, 0
	s_mov_b32 s69, 0x8000
	s_mov_b32 s4, 0x10000
	v_mov_b32_e32 v210, 0
	v_mov_b64_e32 v[28:29], v[12:13]
	v_mov_b64_e32 v[26:27], v[10:11]
	v_mov_b64_e32 v[24:25], v[8:9]
	v_mov_b64_e32 v[22:23], v[6:7]
	v_mov_b64_e32 v[20:21], v[4:5]
	v_mov_b64_e32 v[18:19], v[2:3]
	v_mov_b64_e32 v[16:17], v[0:1]
	v_mov_b64_e32 v[44:45], v[12:13]
	v_mov_b64_e32 v[42:43], v[10:11]
	v_mov_b64_e32 v[40:41], v[8:9]
	v_mov_b64_e32 v[38:39], v[6:7]
	v_mov_b64_e32 v[36:37], v[4:5]
	v_mov_b64_e32 v[34:35], v[2:3]
	v_mov_b64_e32 v[32:33], v[0:1]
	v_mov_b64_e32 v[60:61], v[12:13]
	v_mov_b64_e32 v[58:59], v[10:11]
	v_mov_b64_e32 v[56:57], v[8:9]
	v_mov_b64_e32 v[54:55], v[6:7]
	v_mov_b64_e32 v[52:53], v[4:5]
	v_mov_b64_e32 v[50:51], v[2:3]
	v_mov_b64_e32 v[48:49], v[0:1]
	v_mov_b64_e32 v[76:77], v[12:13]
	v_mov_b64_e32 v[74:75], v[10:11]
	v_mov_b64_e32 v[72:73], v[8:9]
	v_mov_b64_e32 v[70:71], v[6:7]
	v_mov_b64_e32 v[68:69], v[4:5]
	v_mov_b64_e32 v[66:67], v[2:3]
	v_mov_b64_e32 v[64:65], v[0:1]
	s_mov_b32 s71, 0
	s_cmp_lg_u32 s24, 0
	s_cbranch_scc1 .Lyka_ypre
	s_mov_b32 s69, 0x10000
	s_mov_b32 s72, 0x8000
	s_mov_b32 s71, 0
	s_cmp_ge_u32 s68, s65
	s_cselect_b64 s[8:9], -1, 0
.LBB0_1599:
	s_cmp_ge_u32 s68, s59
	s_cbranch_scc1 .Lyka_xtail
	v_add_u32_e32 v0, s72, v208
	ds_read_b128 v[80:83], v0
	ds_read_b128 v[84:87], v0 offset:512
	ds_read_b128 v[6:9], v0 offset:2048
	ds_read_b128 v[112:115], v0 offset:2560
	ds_read_b128 v[10:13], v0 offset:4096
	ds_read_b128 v[116:119], v0 offset:4608
	ds_read_b128 v[2:5], v0 offset:6144
	ds_read_b128 v[120:123], v0 offset:6656
	s_and_b64 vcc, exec, s[8:9]
	s_cbranch_vccnz .LBB0_1608
	s_add_i32 s3, s69, s66
	s_mov_b32 s4, m0
	s_mov_b32 m0, s3
	s_nop 0
	global_load_lds_dwordx4 v[168:169], off
	s_mov_b32 m0, s4
	v_lshl_add_u64 v[14:15], v[168:169], 0, s[28:29]
	s_add_i32 s4, s3, 0x2000
	s_mov_b32 s5, m0
	s_mov_b32 m0, s4
	s_nop 0
	global_load_lds_dwordx4 v[14:15], off
	s_mov_b32 m0, s5
	v_lshl_add_u64 v[14:15], v[168:169], 0, s[40:41]
	s_add_i32 s4, s3, 0x4000
	s_mov_b32 s5, m0
	s_mov_b32 m0, s4
	s_nop 0
	global_load_lds_dwordx4 v[14:15], off
	s_mov_b32 m0, s5
	v_lshl_add_u64 v[14:15], v[168:169], 0, s[80:81]
	s_addk_i32 s3, 0x6000
	s_mov_b32 s4, m0
	s_mov_b32 m0, s3
	s_nop 0
	global_load_lds_dwordx4 v[14:15], off
	s_mov_b32 m0, s4
.LBB0_1608:
	v_pk_add_f32 v[14:15], v[170:171], 0 op_sel_hi:[1,0]
	v_cvt_pk_bf16_f32 v124, v170, v172
	v_pk_add_f32 v[14:15], v[172:173], v[14:15]
	v_cvt_pk_bf16_f32 v125, v174, v176
	v_pk_add_f32 v[14:15], v[174:175], v[14:15]
	v_cvt_pk_bf16_f32 v126, v178, v180
	v_pk_add_f32 v[14:15], v[176:177], v[14:15]
	v_cvt_pk_bf16_f32 v127, v182, v184
	v_pk_add_f32 v[14:15], v[178:179], v[14:15]
	v_cvt_pk_bf16_f32 v128, v186, v188
	v_pk_add_f32 v[14:15], v[180:181], v[14:15]
	v_cvt_pk_bf16_f32 v129, v190, v192
	v_pk_add_f32 v[14:15], v[182:183], v[14:15]
	v_cvt_pk_bf16_f32 v130, v194, v196
	v_pk_add_f32 v[14:15], v[184:185], v[14:15]
	v_cvt_pk_bf16_f32 v131, v198, v200
	v_pk_add_f32 v[14:15], v[186:187], v[14:15]
	v_cvt_pk_bf16_f32 v132, v171, v173
	v_pk_add_f32 v[14:15], v[188:189], v[14:15]
	v_cvt_pk_bf16_f32 v133, v175, v177
	v_pk_add_f32 v[14:15], v[190:191], v[14:15]
	v_cvt_pk_bf16_f32 v134, v179, v181
	v_pk_add_f32 v[14:15], v[192:193], v[14:15]
	v_cvt_pk_bf16_f32 v135, v183, v185
	v_pk_add_f32 v[14:15], v[194:195], v[14:15]
	v_cvt_pk_bf16_f32 v136, v187, v189
	v_pk_add_f32 v[14:15], v[196:197], v[14:15]
	v_cvt_pk_bf16_f32 v137, v191, v193
	v_pk_add_f32 v[14:15], v[198:199], v[14:15]
	v_cvt_pk_bf16_f32 v138, v195, v197
	v_pk_add_f32 v[14:15], v[200:201], v[14:15]
	v_cvt_pk_bf16_f32 v139, v199, v201
	v_add_f32_e32 v0, v14, v15
	s_waitcnt lgkmcnt(7)
	v_mfma_f32_32x32x16_bf16 v[96:111], v[80:83], v[144:147], 0
	v_add_u32_e32 v14, s71, v209
	s_waitcnt lgkmcnt(6)
	v_mfma_f32_32x32x16_bf16 v[80:95], v[84:87], v[144:147], 0
	s_waitcnt lgkmcnt(4)
	v_mfma_f32_32x32x16_bf16 v[80:95], v[112:115], v[148:151], v[80:95]
	v_mfma_f32_32x32x16_bf16 v[96:111], v[6:9], v[148:151], v[96:111]
	s_waitcnt lgkmcnt(2)
	v_mfma_f32_32x32x16_bf16 v[80:95], v[116:119], v[152:155], v[80:95]
	v_mfma_f32_32x32x16_bf16 v[96:111], v[10:13], v[152:155], v[96:111]
	ds_read_b128 v[6:9], v14 offset:16384
	ds_read_b128 v[10:13], v14 offset:16896
	ds_read_b128 v[112:115], v14 offset:17408
	ds_read_b128 v[116:119], v14 offset:17920
	s_waitcnt lgkmcnt(4)
	v_mfma_f32_32x32x16_bf16 v[80:95], v[120:123], v[156:159], v[80:95]
	v_mfma_f32_32x32x16_bf16 v[96:111], v[2:5], v[156:159], v[96:111]
	s_waitcnt lgkmcnt(3)
	v_mfma_f32_32x32x16_bf16 v[64:79], v[6:9], v[124:127], v[64:79]
	ds_read_b128 v[2:5], v14 offset:20480
	s_add_i32 s3, s68, 3
	s_and_b32 s69, s3, 3
	s_lshl_b32 s69, s69, 15
	s_add_i32 s72, s68, 2
	s_and_b32 s72, s72, 3
	s_lshl_b32 s72, s72, 15
	s_add_i32 s71, s68, 1
	s_and_b32 s71, s71, 3
	s_lshl_b32 s71, s71, 15
	s_add_i32 s3, s68, 1
	s_cmp_ge_u32 s3, s65
	s_cselect_b64 s[8:9], -1, 0
	v_exp_f32_e32 v170, v96
	v_exp_f32_e32 v172, v97
	s_waitcnt lgkmcnt(3)
	v_mfma_f32_32x32x16_bf16 v[48:63], v[10:13], v[124:127], v[48:63]
	ds_read_b128 v[6:9], v14 offset:20992
	v_exp_f32_e32 v174, v98
	v_exp_f32_e32 v176, v99
	s_waitcnt lgkmcnt(3)
	v_mfma_f32_32x32x16_bf16 v[32:47], v[112:115], v[124:127], v[32:47]
	ds_read_b128 v[10:13], v14 offset:21504
	v_exp_f32_e32 v178, v100
	v_exp_f32_e32 v180, v101
	s_waitcnt lgkmcnt(3)
	v_mfma_f32_32x32x16_bf16 v[16:31], v[116:119], v[124:127], v[16:31]
	ds_read_b128 v[96:99], v14 offset:22016
	v_exp_f32_e32 v182, v102
	v_exp_f32_e32 v184, v103
	s_waitcnt lgkmcnt(3)
	v_mfma_f32_32x32x16_bf16 v[64:79], v[2:5], v[128:131], v[64:79]
	ds_read_b128 v[2:5], v14 offset:24576
	v_exp_f32_e32 v186, v104
	v_exp_f32_e32 v188, v105
	s_waitcnt lgkmcnt(3)
	v_mfma_f32_32x32x16_bf16 v[48:63], v[6:9], v[128:131], v[48:63]
	ds_read_b128 v[6:9], v14 offset:25088
	v_exp_f32_e32 v190, v106
	v_exp_f32_e32 v192, v107
	s_waitcnt lgkmcnt(3)
	v_mfma_f32_32x32x16_bf16 v[32:47], v[10:13], v[128:131], v[32:47]
	ds_read_b128 v[10:13], v14 offset:25600
	v_exp_f32_e32 v194, v108
	v_exp_f32_e32 v196, v109
	s_waitcnt lgkmcnt(3)
	v_mfma_f32_32x32x16_bf16 v[16:31], v[96:99], v[128:131], v[16:31]
	ds_read_b128 v[96:99], v14 offset:26112
	v_exp_f32_e32 v198, v110
	v_exp_f32_e32 v200, v111
	s_waitcnt lgkmcnt(3)
	v_mfma_f32_32x32x16_bf16 v[64:79], v[2:5], v[132:135], v[64:79]
	ds_read_b128 v[2:5], v14 offset:28672
	v_exp_f32_e32 v171, v80
	v_exp_f32_e32 v173, v81
	s_waitcnt lgkmcnt(3)
	v_mfma_f32_32x32x16_bf16 v[48:63], v[6:9], v[132:135], v[48:63]
	ds_read_b128 v[6:9], v14 offset:29184
	v_exp_f32_e32 v175, v82
	v_exp_f32_e32 v177, v83
	s_waitcnt lgkmcnt(3)
	v_mfma_f32_32x32x16_bf16 v[32:47], v[10:13], v[132:135], v[32:47]
	ds_read_b128 v[10:13], v14 offset:29696
	v_exp_f32_e32 v179, v84
	v_exp_f32_e32 v181, v85
	s_waitcnt lgkmcnt(3)
	v_mfma_f32_32x32x16_bf16 v[16:31], v[96:99], v[132:135], v[16:31]
	ds_read_b128 v[80:83], v14 offset:30208
	v_exp_f32_e32 v183, v86
	v_exp_f32_e32 v185, v87
	s_waitcnt lgkmcnt(3)
	v_mfma_f32_32x32x16_bf16 v[64:79], v[2:5], v[136:139], v[64:79]
	v_exp_f32_e32 v187, v88
	v_exp_f32_e32 v189, v89
	s_waitcnt lgkmcnt(2)
	v_mfma_f32_32x32x16_bf16 v[48:63], v[6:9], v[136:139], v[48:63]
	v_exp_f32_e32 v191, v90
	v_exp_f32_e32 v193, v91
	s_waitcnt lgkmcnt(1)
	v_mfma_f32_32x32x16_bf16 v[32:47], v[10:13], v[136:139], v[32:47]
	v_exp_f32_e32 v195, v92
	v_exp_f32_e32 v197, v93
	s_waitcnt lgkmcnt(0)
	v_mfma_f32_32x32x16_bf16 v[16:31], v[80:83], v[136:139], v[16:31]
	v_exp_f32_e32 v199, v94
	v_exp_f32_e32 v201, v95
	v_add_f32_e32 v210, v210, v0
	s_branch .LBB0_1610

.Lyka_pre:
	s_mov_b64 s[4:5], 0x8000
	v_lshl_add_u64 v[168:169], v[168:169], 0, s[4:5]
	s_mov_b32 s69, 0x18000
	s_mov_b32 s72, 0x8000
	s_mov_b32 s71, 0
.Lyka_ytop:
	s_cmp_ge_u32 s68, s59
	s_cbranch_scc1 .Lyka_ytail
	v_add_u32_e32 v0, s72, v208
	ds_read_b128 v[80:83], v0
	ds_read_b128 v[84:87], v0 offset:512
	ds_read_b128 v[6:9], v0 offset:2048
	ds_read_b128 v[112:115], v0 offset:2560
	ds_read_b128 v[10:13], v0 offset:4096
	ds_read_b128 v[116:119], v0 offset:4608
	ds_read_b128 v[2:5], v0 offset:6144
	ds_read_b128 v[120:123], v0 offset:6656
	v_pk_add_f32 v[14:15], v[170:171], 0 op_sel_hi:[1,0]
	v_cvt_pk_bf16_f32 v124, v170, v172
	v_pk_add_f32 v[14:15], v[172:173], v[14:15]
	v_cvt_pk_bf16_f32 v125, v174, v176
	v_pk_add_f32 v[14:15], v[174:175], v[14:15]
	v_cvt_pk_bf16_f32 v126, v178, v180
	v_pk_add_f32 v[14:15], v[176:177], v[14:15]
	v_cvt_pk_bf16_f32 v127, v182, v184
	v_pk_add_f32 v[14:15], v[178:179], v[14:15]
	v_cvt_pk_bf16_f32 v128, v186, v188
	v_pk_add_f32 v[14:15], v[180:181], v[14:15]
	v_cvt_pk_bf16_f32 v129, v190, v192
	v_pk_add_f32 v[14:15], v[182:183], v[14:15]
	v_cvt_pk_bf16_f32 v130, v194, v196
	v_pk_add_f32 v[14:15], v[184:185], v[14:15]
	v_cvt_pk_bf16_f32 v131, v198, v200
	v_pk_add_f32 v[14:15], v[186:187], v[14:15]
	v_cvt_pk_bf16_f32 v132, v171, v173
	v_pk_add_f32 v[14:15], v[188:189], v[14:15]
	v_cvt_pk_bf16_f32 v133, v175, v177
	v_pk_add_f32 v[14:15], v[190:191], v[14:15]
	v_cvt_pk_bf16_f32 v134, v179, v181
	v_pk_add_f32 v[14:15], v[192:193], v[14:15]
	v_cvt_pk_bf16_f32 v135, v183, v185
	v_pk_add_f32 v[14:15], v[194:195], v[14:15]
	v_cvt_pk_bf16_f32 v136, v187, v189
	v_pk_add_f32 v[14:15], v[196:197], v[14:15]
	v_cvt_pk_bf16_f32 v137, v191, v193
	v_pk_add_f32 v[14:15], v[198:199], v[14:15]
	v_cvt_pk_bf16_f32 v138, v195, v197
	v_pk_add_f32 v[14:15], v[200:201], v[14:15]
	v_cvt_pk_bf16_f32 v139, v199, v201
	v_add_f32_e32 v0, v14, v15
	s_waitcnt lgkmcnt(7)
	v_mfma_f32_32x32x16_bf16 v[96:111], v[80:83], v[144:147], 0
	v_add_u32_e32 v14, s71, v209
	s_waitcnt lgkmcnt(6)
	v_mfma_f32_32x32x16_bf16 v[80:95], v[84:87], v[144:147], 0
	s_waitcnt lgkmcnt(4)
	v_mfma_f32_32x32x16_bf16 v[80:95], v[112:115], v[148:151], v[80:95]
	v_mfma_f32_32x32x16_bf16 v[96:111], v[6:9], v[148:151], v[96:111]
	s_waitcnt lgkmcnt(2)
	v_mfma_f32_32x32x16_bf16 v[80:95], v[116:119], v[152:155], v[80:95]
	v_mfma_f32_32x32x16_bf16 v[96:111], v[10:13], v[152:155], v[96:111]
	ds_read_b128 v[6:9], v14 offset:16384
	ds_read_b128 v[10:13], v14 offset:16896
	ds_read_b128 v[112:115], v14 offset:17408
	ds_read_b128 v[116:119], v14 offset:17920
	s_waitcnt lgkmcnt(4)
	v_mfma_f32_32x32x16_bf16 v[80:95], v[120:123], v[156:159], v[80:95]
	v_mfma_f32_32x32x16_bf16 v[96:111], v[2:5], v[156:159], v[96:111]
	s_waitcnt vmcnt(0)
	s_barrier
	s_add_i32 s3, s68, 3
	s_cmp_lt_u32 s3, s67
	s_cbranch_scc0 .Lyka_ynodma
	s_add_i32 s3, s69, s66
	s_mov_b32 s4, m0
	s_mov_b32 m0, s3
	s_nop 0
	global_load_lds_dwordx4 v[168:169], off
	s_mov_b32 m0, s4
	v_lshl_add_u64 v[120:121], v[168:169], 0, s[28:29]
	s_add_i32 s4, s3, 0x2000
	s_mov_b32 s5, m0
	s_mov_b32 m0, s4
	s_nop 0
	global_load_lds_dwordx4 v[120:121], off
	s_mov_b32 m0, s5
	v_lshl_add_u64 v[120:121], v[168:169], 0, s[40:41]
	s_add_i32 s4, s3, 0x4000
	s_mov_b32 s5, m0
	s_mov_b32 m0, s4
	s_nop 0
	global_load_lds_dwordx4 v[120:121], off
	s_mov_b32 m0, s5
	v_lshl_add_u64 v[120:121], v[168:169], 0, s[80:81]
	s_addk_i32 s3, 0x6000
	s_mov_b32 s4, m0
	s_mov_b32 m0, s3
	s_nop 0
	global_load_lds_dwordx4 v[120:121], off
	s_mov_b32 m0, s4
.Lyka_ynodma:
	s_waitcnt lgkmcnt(3)
	v_mfma_f32_32x32x16_bf16 v[64:79], v[6:9], v[124:127], v[64:79]
	ds_read_b128 v[2:5], v14 offset:20480
	s_add_i32 s3, s68, 4
	s_and_b32 s69, s3, 3
	s_lshl_b32 s69, s69, 15
	s_add_i32 s72, s68, 2
	s_and_b32 s72, s72, 3
	s_lshl_b32 s72, s72, 15
	s_add_i32 s71, s68, 1
	s_and_b32 s71, s71, 3
	s_lshl_b32 s71, s71, 15
	v_exp_f32_e32 v170, v96
	v_exp_f32_e32 v172, v97
	s_waitcnt lgkmcnt(3)
	v_mfma_f32_32x32x16_bf16 v[48:63], v[10:13], v[124:127], v[48:63]
	ds_read_b128 v[6:9], v14 offset:20992
	v_exp_f32_e32 v174, v98
	v_exp_f32_e32 v176, v99
	s_waitcnt lgkmcnt(3)
	v_mfma_f32_32x32x16_bf16 v[32:47], v[112:115], v[124:127], v[32:47]
	ds_read_b128 v[10:13], v14 offset:21504
	v_exp_f32_e32 v178, v100
	v_exp_f32_e32 v180, v101
	s_waitcnt lgkmcnt(3)
	v_mfma_f32_32x32x16_bf16 v[16:31], v[116:119], v[124:127], v[16:31]
	ds_read_b128 v[96:99], v14 offset:22016
	v_exp_f32_e32 v182, v102
	v_exp_f32_e32 v184, v103
	s_waitcnt lgkmcnt(3)
	v_mfma_f32_32x32x16_bf16 v[64:79], v[2:5], v[128:131], v[64:79]
	ds_read_b128 v[2:5], v14 offset:24576
	v_exp_f32_e32 v186, v104
	v_exp_f32_e32 v188, v105
	s_waitcnt lgkmcnt(3)
	v_mfma_f32_32x32x16_bf16 v[48:63], v[6:9], v[128:131], v[48:63]
	ds_read_b128 v[6:9], v14 offset:25088
	v_exp_f32_e32 v190, v106
	v_exp_f32_e32 v192, v107
	s_waitcnt lgkmcnt(3)
	v_mfma_f32_32x32x16_bf16 v[32:47], v[10:13], v[128:131], v[32:47]
	ds_read_b128 v[10:13], v14 offset:25600
	v_exp_f32_e32 v194, v108
	v_exp_f32_e32 v196, v109
	s_waitcnt lgkmcnt(3)
	v_mfma_f32_32x32x16_bf16 v[16:31], v[96:99], v[128:131], v[16:31]
	ds_read_b128 v[96:99], v14 offset:26112
	v_exp_f32_e32 v198, v110
	v_exp_f32_e32 v200, v111
	s_waitcnt lgkmcnt(3)
	v_mfma_f32_32x32x16_bf16 v[64:79], v[2:5], v[132:135], v[64:79]
	ds_read_b128 v[2:5], v14 offset:28672
	v_exp_f32_e32 v171, v80
	v_exp_f32_e32 v173, v81
	s_waitcnt lgkmcnt(3)
	v_mfma_f32_32x32x16_bf16 v[48:63], v[6:9], v[132:135], v[48:63]
	ds_read_b128 v[6:9], v14 offset:29184
	v_exp_f32_e32 v175, v82
	v_exp_f32_e32 v177, v83
	s_waitcnt lgkmcnt(3)
	v_mfma_f32_32x32x16_bf16 v[32:47], v[10:13], v[132:135], v[32:47]
	ds_read_b128 v[10:13], v14 offset:29696
	v_exp_f32_e32 v179, v84
	v_exp_f32_e32 v181, v85
	s_waitcnt lgkmcnt(3)
	v_mfma_f32_32x32x16_bf16 v[16:31], v[96:99], v[132:135], v[16:31]
	ds_read_b128 v[80:83], v14 offset:30208
	v_exp_f32_e32 v183, v86
	v_exp_f32_e32 v185, v87
	s_waitcnt lgkmcnt(3)
	v_mfma_f32_32x32x16_bf16 v[64:79], v[2:5], v[136:139], v[64:79]
	v_exp_f32_e32 v187, v88
	v_exp_f32_e32 v189, v89
	s_waitcnt lgkmcnt(2)
	v_mfma_f32_32x32x16_bf16 v[48:63], v[6:9], v[136:139], v[48:63]
	v_exp_f32_e32 v191, v90
	v_exp_f32_e32 v193, v91
	s_waitcnt lgkmcnt(1)
	v_mfma_f32_32x32x16_bf16 v[32:47], v[10:13], v[136:139], v[32:47]
	v_exp_f32_e32 v195, v92
	v_exp_f32_e32 v197, v93
	s_waitcnt lgkmcnt(0)
	v_mfma_f32_32x32x16_bf16 v[16:31], v[80:83], v[136:139], v[16:31]
	v_exp_f32_e32 v199, v94
	v_exp_f32_e32 v201, v95
	v_add_f32_e32 v210, v210, v0
	s_branch .Lyka_ynext

.LBB0_2151:
	s_lshl_b32 s67, s4, 1
	s_lshl_b32 s3, s5, 10
	s_lshr_b32 s66, s66, 6
	s_ashr_i32 s5, s3, 31
	s_add_i32 s68, s3, 0
	s_add_i32 s69, s67, 2
	s_add_u32 s4, s88, s3
	s_nop 1
	v_exp_f32_e32 v168, v2
	s_nop 0
	v_exp_f32_e32 v169, v18
	v_exp_f32_e32 v172, v3
	v_exp_f32_e32 v173, v19
	v_exp_f32_e32 v174, v4
	v_exp_f32_e32 v175, v20
	v_exp_f32_e32 v176, v5
	v_exp_f32_e32 v177, v21
	v_exp_f32_e32 v178, v6
	v_exp_f32_e32 v179, v22
	v_exp_f32_e32 v180, v7
	v_exp_f32_e32 v181, v23
	v_exp_f32_e32 v182, v8
	v_exp_f32_e32 v183, v24
	v_exp_f32_e32 v184, v9
	v_exp_f32_e32 v185, v25
	v_exp_f32_e32 v186, v10
	v_exp_f32_e32 v187, v26
	v_exp_f32_e32 v188, v11
	v_exp_f32_e32 v189, v27
	v_exp_f32_e32 v190, v12
	v_exp_f32_e32 v191, v28
	v_exp_f32_e32 v192, v13
	v_exp_f32_e32 v193, v29
	v_exp_f32_e32 v194, v14
	v_exp_f32_e32 v195, v30
	v_exp_f32_e32 v196, v15
	v_exp_f32_e32 v197, v31
	v_exp_f32_e32 v198, v16
	v_exp_f32_e32 v199, v32
	v_exp_f32_e32 v200, v17
	v_exp_f32_e32 v201, v33
	v_lshlrev_b32_e32 v2, 11, v163
	s_addc_u32 s5, s89, s5
	v_add3_u32 v209, 0, v2, v34
	v_lshlrev_b32_e32 v2, 4, v207
	v_mov_b32_e32 v3, v1
	v_lshl_add_u64 v[4:5], s[4:5], 0, v[0:1]
	v_mov_b32_e32 v14, v1
	v_mov_b32_e32 v15, v1
	v_lshl_add_u64 v[170:171], v[4:5], 0, v[2:3]
	v_mov_b32_e32 v0, v1
	v_mov_b32_e32 v2, v1
	v_mov_b32_e32 v4, v1
	v_mov_b32_e32 v5, v1
	v_mov_b32_e32 v6, v1
	v_mov_b32_e32 v7, v1
	v_mov_b32_e32 v8, v1
	v_mov_b32_e32 v9, v1
	v_mov_b32_e32 v10, v1
	v_mov_b32_e32 v11, v1
	v_mov_b32_e32 v12, v1
	v_mov_b32_e32 v13, v1
	v_mov_b64_e32 v[30:31], v[14:15]
	v_mov_b64_e32 v[46:47], v[14:15]
	v_mov_b64_e32 v[62:63], v[14:15]
	v_mov_b64_e32 v[78:79], v[14:15]
	s_mov_b32 s78, 0
	s_mov_b32 s79, 0x8000
	s_mov_b32 s4, 0x10000
	v_mov_b32_e32 v210, 0
	v_mov_b64_e32 v[28:29], v[12:13]
	v_mov_b64_e32 v[26:27], v[10:11]
	v_mov_b64_e32 v[24:25], v[8:9]
	v_mov_b64_e32 v[22:23], v[6:7]
	v_mov_b64_e32 v[20:21], v[4:5]
	v_mov_b64_e32 v[18:19], v[2:3]
	v_mov_b64_e32 v[16:17], v[0:1]
	v_mov_b64_e32 v[44:45], v[12:13]
	v_mov_b64_e32 v[42:43], v[10:11]
	v_mov_b64_e32 v[40:41], v[8:9]
	v_mov_b64_e32 v[38:39], v[6:7]
	v_mov_b64_e32 v[36:37], v[4:5]
	v_mov_b64_e32 v[34:35], v[2:3]
	v_mov_b64_e32 v[32:33], v[0:1]
	v_mov_b64_e32 v[60:61], v[12:13]
	v_mov_b64_e32 v[58:59], v[10:11]
	v_mov_b64_e32 v[56:57], v[8:9]
	v_mov_b64_e32 v[54:55], v[6:7]
	v_mov_b64_e32 v[52:53], v[4:5]
	v_mov_b64_e32 v[50:51], v[2:3]
	v_mov_b64_e32 v[48:49], v[0:1]
	v_mov_b64_e32 v[76:77], v[12:13]
	v_mov_b64_e32 v[74:75], v[10:11]
	v_mov_b64_e32 v[72:73], v[8:9]
	v_mov_b64_e32 v[70:71], v[6:7]
	v_mov_b64_e32 v[68:69], v[4:5]
	v_mov_b64_e32 v[66:67], v[2:3]
	v_mov_b64_e32 v[64:65], v[0:1]
	s_mov_b32 s80, 0
	s_cmp_lg_u32 s12, 0
	s_cbranch_scc1 .Lykb_ypre
	s_mov_b32 s79, 0x10000
	s_mov_b32 s81, 0x8000
	s_mov_b32 s80, 0
	s_cmp_ge_u32 s78, s67
	s_cselect_b64 s[8:9], -1, 0
.LBB0_2152:
	s_cmp_ge_u32 s78, s66
	s_cbranch_scc1 .Lykb_xtail
	v_add_u32_e32 v0, s81, v208
	ds_read_b128 v[80:83], v0
	ds_read_b128 v[84:87], v0 offset:512
	ds_read_b128 v[6:9], v0 offset:2048
	ds_read_b128 v[112:115], v0 offset:2560
	ds_read_b128 v[10:13], v0 offset:4096
	ds_read_b128 v[116:119], v0 offset:4608
	ds_read_b128 v[2:5], v0 offset:6144
	ds_read_b128 v[120:123], v0 offset:6656
	s_and_b64 vcc, exec, s[8:9]
	s_cbranch_vccnz .LBB0_2161
	s_add_i32 s3, s79, s68
	s_mov_b32 s4, m0
	s_mov_b32 m0, s3
	s_nop 0
	global_load_lds_dwordx4 v[170:171], off
	s_mov_b32 m0, s4
	v_lshl_add_u64 v[14:15], v[170:171], 0, s[24:25]
	s_add_i32 s4, s3, 0x2000
	s_mov_b32 s5, m0
	s_mov_b32 m0, s4
	s_nop 0
	global_load_lds_dwordx4 v[14:15], off
	s_mov_b32 m0, s5
	v_lshl_add_u64 v[14:15], v[170:171], 0, s[26:27]
	s_add_i32 s4, s3, 0x4000
	s_mov_b32 s5, m0
	s_mov_b32 m0, s4
	s_nop 0
	global_load_lds_dwordx4 v[14:15], off
	s_mov_b32 m0, s5
	v_lshl_add_u64 v[14:15], v[170:171], 0, s[44:45]
	s_addk_i32 s3, 0x6000
	s_mov_b32 s4, m0
	s_mov_b32 m0, s3
	s_nop 0
	global_load_lds_dwordx4 v[14:15], off
	s_mov_b32 m0, s4
.LBB0_2161:
	v_pk_add_f32 v[14:15], v[168:169], 0 op_sel_hi:[1,0]
	v_cvt_pk_bf16_f32 v124, v168, v172
	v_pk_add_f32 v[14:15], v[172:173], v[14:15]
	v_cvt_pk_bf16_f32 v125, v174, v176
	v_pk_add_f32 v[14:15], v[174:175], v[14:15]
	v_cvt_pk_bf16_f32 v126, v178, v180
	v_pk_add_f32 v[14:15], v[176:177], v[14:15]
	v_cvt_pk_bf16_f32 v127, v182, v184
	v_pk_add_f32 v[14:15], v[178:179], v[14:15]
	v_cvt_pk_bf16_f32 v128, v186, v188
	v_pk_add_f32 v[14:15], v[180:181], v[14:15]
	v_cvt_pk_bf16_f32 v129, v190, v192
	v_pk_add_f32 v[14:15], v[182:183], v[14:15]
	v_cvt_pk_bf16_f32 v130, v194, v196
	v_pk_add_f32 v[14:15], v[184:185], v[14:15]
	v_cvt_pk_bf16_f32 v131, v198, v200
	v_pk_add_f32 v[14:15], v[186:187], v[14:15]
	v_cvt_pk_bf16_f32 v132, v169, v173
	v_pk_add_f32 v[14:15], v[188:189], v[14:15]
	v_cvt_pk_bf16_f32 v133, v175, v177
	v_pk_add_f32 v[14:15], v[190:191], v[14:15]
	v_cvt_pk_bf16_f32 v134, v179, v181
	v_pk_add_f32 v[14:15], v[192:193], v[14:15]
	v_cvt_pk_bf16_f32 v135, v183, v185
	v_pk_add_f32 v[14:15], v[194:195], v[14:15]
	v_cvt_pk_bf16_f32 v136, v187, v189
	v_pk_add_f32 v[14:15], v[196:197], v[14:15]
	v_cvt_pk_bf16_f32 v137, v191, v193
	v_pk_add_f32 v[14:15], v[198:199], v[14:15]
	v_cvt_pk_bf16_f32 v138, v195, v197
	v_pk_add_f32 v[14:15], v[200:201], v[14:15]
	v_cvt_pk_bf16_f32 v139, v199, v201
	v_add_f32_e32 v0, v14, v15
	s_waitcnt lgkmcnt(7)
	v_mfma_f32_32x32x16_bf16 v[96:111], v[80:83], v[144:147], 0
	v_add_u32_e32 v14, s80, v209
	s_waitcnt lgkmcnt(6)
	v_mfma_f32_32x32x16_bf16 v[80:95], v[84:87], v[144:147], 0
	s_waitcnt lgkmcnt(4)
	v_mfma_f32_32x32x16_bf16 v[80:95], v[112:115], v[148:151], v[80:95]
	v_mfma_f32_32x32x16_bf16 v[96:111], v[6:9], v[148:151], v[96:111]
	s_waitcnt lgkmcnt(2)
	v_mfma_f32_32x32x16_bf16 v[80:95], v[116:119], v[152:155], v[80:95]
	v_mfma_f32_32x32x16_bf16 v[96:111], v[10:13], v[152:155], v[96:111]
	ds_read_b128 v[6:9], v14 offset:16384
	ds_read_b128 v[10:13], v14 offset:16896
	ds_read_b128 v[112:115], v14 offset:17408
	ds_read_b128 v[116:119], v14 offset:17920
	s_waitcnt lgkmcnt(4)
	v_mfma_f32_32x32x16_bf16 v[80:95], v[120:123], v[156:159], v[80:95]
	v_mfma_f32_32x32x16_bf16 v[96:111], v[2:5], v[156:159], v[96:111]
	s_waitcnt lgkmcnt(3)
	v_mfma_f32_32x32x16_bf16 v[64:79], v[6:9], v[124:127], v[64:79]
	ds_read_b128 v[2:5], v14 offset:20480
	s_add_i32 s3, s78, 3
	s_and_b32 s79, s3, 3
	s_lshl_b32 s79, s79, 15
	s_add_i32 s81, s78, 2
	s_and_b32 s81, s81, 3
	s_lshl_b32 s81, s81, 15
	s_add_i32 s80, s78, 1
	s_and_b32 s80, s80, 3
	s_lshl_b32 s80, s80, 15
	s_add_i32 s3, s78, 1
	s_cmp_ge_u32 s3, s67
	s_cselect_b64 s[8:9], -1, 0
	v_exp_f32_e32 v168, v96
	v_exp_f32_e32 v172, v97
	s_waitcnt lgkmcnt(3)
	v_mfma_f32_32x32x16_bf16 v[48:63], v[10:13], v[124:127], v[48:63]
	ds_read_b128 v[6:9], v14 offset:20992
	v_exp_f32_e32 v174, v98
	v_exp_f32_e32 v176, v99
	s_waitcnt lgkmcnt(3)
	v_mfma_f32_32x32x16_bf16 v[32:47], v[112:115], v[124:127], v[32:47]
	ds_read_b128 v[10:13], v14 offset:21504
	v_exp_f32_e32 v178, v100
	v_exp_f32_e32 v180, v101
	s_waitcnt lgkmcnt(3)
	v_mfma_f32_32x32x16_bf16 v[16:31], v[116:119], v[124:127], v[16:31]
	ds_read_b128 v[96:99], v14 offset:22016
	v_exp_f32_e32 v182, v102
	v_exp_f32_e32 v184, v103
	s_waitcnt lgkmcnt(3)
	v_mfma_f32_32x32x16_bf16 v[64:79], v[2:5], v[128:131], v[64:79]
	ds_read_b128 v[100:103], v14 offset:24576
	v_exp_f32_e32 v186, v104
	v_exp_f32_e32 v188, v105
	s_waitcnt lgkmcnt(3)
	v_mfma_f32_32x32x16_bf16 v[48:63], v[6:9], v[128:131], v[48:63]
	ds_read_b128 v[2:5], v14 offset:25088
	v_exp_f32_e32 v190, v106
	v_exp_f32_e32 v192, v107
	s_waitcnt lgkmcnt(3)
	v_mfma_f32_32x32x16_bf16 v[32:47], v[10:13], v[128:131], v[32:47]
	ds_read_b128 v[6:9], v14 offset:25600
	v_exp_f32_e32 v194, v108
	v_exp_f32_e32 v196, v109
	s_waitcnt lgkmcnt(3)
	v_mfma_f32_32x32x16_bf16 v[16:31], v[96:99], v[128:131], v[16:31]
	ds_read_b128 v[10:13], v14 offset:26112
	v_exp_f32_e32 v198, v110
	v_exp_f32_e32 v200, v111
	s_waitcnt lgkmcnt(3)
	v_mfma_f32_32x32x16_bf16 v[64:79], v[100:103], v[132:135], v[64:79]
	ds_read_b128 v[96:99], v14 offset:28672
	v_exp_f32_e32 v169, v80
	v_exp_f32_e32 v173, v81
	s_waitcnt lgkmcnt(3)
	v_mfma_f32_32x32x16_bf16 v[48:63], v[2:5], v[132:135], v[48:63]
	ds_read_b128 v[100:103], v14 offset:29184
	v_exp_f32_e32 v175, v82
	v_exp_f32_e32 v177, v83
	s_waitcnt lgkmcnt(3)
	v_mfma_f32_32x32x16_bf16 v[32:47], v[6:9], v[132:135], v[32:47]
	ds_read_b128 v[2:5], v14 offset:29696
	v_exp_f32_e32 v179, v84
	v_exp_f32_e32 v181, v85
	s_waitcnt lgkmcnt(3)
	v_mfma_f32_32x32x16_bf16 v[16:31], v[10:13], v[132:135], v[16:31]
	ds_read_b128 v[6:9], v14 offset:30208
	v_exp_f32_e32 v183, v86
	v_exp_f32_e32 v185, v87
	s_waitcnt lgkmcnt(3)
	v_mfma_f32_32x32x16_bf16 v[64:79], v[96:99], v[136:139], v[64:79]
	v_exp_f32_e32 v187, v88
	v_exp_f32_e32 v189, v89
	s_waitcnt lgkmcnt(2)
	v_mfma_f32_32x32x16_bf16 v[48:63], v[100:103], v[136:139], v[48:63]
	v_exp_f32_e32 v191, v90
	v_exp_f32_e32 v193, v91
	s_waitcnt lgkmcnt(1)
	v_mfma_f32_32x32x16_bf16 v[32:47], v[2:5], v[136:139], v[32:47]
	v_exp_f32_e32 v195, v92
	v_exp_f32_e32 v197, v93
	s_waitcnt lgkmcnt(0)
	v_mfma_f32_32x32x16_bf16 v[16:31], v[6:9], v[136:139], v[16:31]
	v_exp_f32_e32 v199, v94
	v_exp_f32_e32 v201, v95
	v_add_f32_e32 v210, v210, v0
	s_branch .LBB0_2163

.Lykb_pre:
	s_mov_b64 s[4:5], 0x8000
	v_lshl_add_u64 v[170:171], v[170:171], 0, s[4:5]
	s_mov_b32 s79, 0x18000
	s_mov_b32 s81, 0x8000
	s_mov_b32 s80, 0
.Lykb_ytop:
	s_cmp_ge_u32 s78, s66
	s_cbranch_scc1 .Lykb_ytail
	v_add_u32_e32 v0, s81, v208
	ds_read_b128 v[80:83], v0
	ds_read_b128 v[84:87], v0 offset:512
	ds_read_b128 v[6:9], v0 offset:2048
	ds_read_b128 v[112:115], v0 offset:2560
	ds_read_b128 v[10:13], v0 offset:4096
	ds_read_b128 v[116:119], v0 offset:4608
	ds_read_b128 v[2:5], v0 offset:6144
	ds_read_b128 v[120:123], v0 offset:6656
	v_pk_add_f32 v[14:15], v[168:169], 0 op_sel_hi:[1,0]
	v_cvt_pk_bf16_f32 v124, v168, v172
	v_pk_add_f32 v[14:15], v[172:173], v[14:15]
	v_cvt_pk_bf16_f32 v125, v174, v176
	v_pk_add_f32 v[14:15], v[174:175], v[14:15]
	v_cvt_pk_bf16_f32 v126, v178, v180
	v_pk_add_f32 v[14:15], v[176:177], v[14:15]
	v_cvt_pk_bf16_f32 v127, v182, v184
	v_pk_add_f32 v[14:15], v[178:179], v[14:15]
	v_cvt_pk_bf16_f32 v128, v186, v188
	v_pk_add_f32 v[14:15], v[180:181], v[14:15]
	v_cvt_pk_bf16_f32 v129, v190, v192
	v_pk_add_f32 v[14:15], v[182:183], v[14:15]
	v_cvt_pk_bf16_f32 v130, v194, v196
	v_pk_add_f32 v[14:15], v[184:185], v[14:15]
	v_cvt_pk_bf16_f32 v131, v198, v200
	v_pk_add_f32 v[14:15], v[186:187], v[14:15]
	v_cvt_pk_bf16_f32 v132, v169, v173
	v_pk_add_f32 v[14:15], v[188:189], v[14:15]
	v_cvt_pk_bf16_f32 v133, v175, v177
	v_pk_add_f32 v[14:15], v[190:191], v[14:15]
	v_cvt_pk_bf16_f32 v134, v179, v181
	v_pk_add_f32 v[14:15], v[192:193], v[14:15]
	v_cvt_pk_bf16_f32 v135, v183, v185
	v_pk_add_f32 v[14:15], v[194:195], v[14:15]
	v_cvt_pk_bf16_f32 v136, v187, v189
	v_pk_add_f32 v[14:15], v[196:197], v[14:15]
	v_cvt_pk_bf16_f32 v137, v191, v193
	v_pk_add_f32 v[14:15], v[198:199], v[14:15]
	v_cvt_pk_bf16_f32 v138, v195, v197
	v_pk_add_f32 v[14:15], v[200:201], v[14:15]
	v_cvt_pk_bf16_f32 v139, v199, v201
	v_add_f32_e32 v0, v14, v15
	s_waitcnt lgkmcnt(7)
	v_mfma_f32_32x32x16_bf16 v[96:111], v[80:83], v[144:147], 0
	v_add_u32_e32 v14, s80, v209
	s_waitcnt lgkmcnt(6)
	v_mfma_f32_32x32x16_bf16 v[80:95], v[84:87], v[144:147], 0
	s_waitcnt lgkmcnt(4)
	v_mfma_f32_32x32x16_bf16 v[80:95], v[112:115], v[148:151], v[80:95]
	v_mfma_f32_32x32x16_bf16 v[96:111], v[6:9], v[148:151], v[96:111]
	s_waitcnt lgkmcnt(2)
	v_mfma_f32_32x32x16_bf16 v[80:95], v[116:119], v[152:155], v[80:95]
	v_mfma_f32_32x32x16_bf16 v[96:111], v[10:13], v[152:155], v[96:111]
	ds_read_b128 v[6:9], v14 offset:16384
	ds_read_b128 v[10:13], v14 offset:16896
	ds_read_b128 v[112:115], v14 offset:17408
	ds_read_b128 v[116:119], v14 offset:17920
	s_waitcnt lgkmcnt(4)
	v_mfma_f32_32x32x16_bf16 v[80:95], v[120:123], v[156:159], v[80:95]
	v_mfma_f32_32x32x16_bf16 v[96:111], v[2:5], v[156:159], v[96:111]
	s_waitcnt vmcnt(0)
	s_barrier
	s_add_i32 s3, s78, 3
	s_cmp_lt_u32 s3, s69
	s_cbranch_scc0 .Lykb_ynodma
	s_add_i32 s3, s79, s68
	s_mov_b32 s4, m0
	s_mov_b32 m0, s3
	s_nop 0
	global_load_lds_dwordx4 v[170:171], off
	s_mov_b32 m0, s4
	v_lshl_add_u64 v[120:121], v[170:171], 0, s[24:25]
	s_add_i32 s4, s3, 0x2000
	s_mov_b32 s5, m0
	s_mov_b32 m0, s4
	s_nop 0
	global_load_lds_dwordx4 v[120:121], off
	s_mov_b32 m0, s5
	v_lshl_add_u64 v[120:121], v[170:171], 0, s[26:27]
	s_add_i32 s4, s3, 0x4000
	s_mov_b32 s5, m0
	s_mov_b32 m0, s4
	s_nop 0
	global_load_lds_dwordx4 v[120:121], off
	s_mov_b32 m0, s5
	v_lshl_add_u64 v[120:121], v[170:171], 0, s[44:45]
	s_addk_i32 s3, 0x6000
	s_mov_b32 s4, m0
	s_mov_b32 m0, s3
	s_nop 0
	global_load_lds_dwordx4 v[120:121], off
	s_mov_b32 m0, s4
.Lykb_ynodma:
	s_waitcnt lgkmcnt(3)
	v_mfma_f32_32x32x16_bf16 v[64:79], v[6:9], v[124:127], v[64:79]
	ds_read_b128 v[2:5], v14 offset:20480
	s_add_i32 s3, s78, 4
	s_and_b32 s79, s3, 3
	s_lshl_b32 s79, s79, 15
	s_add_i32 s81, s78, 2
	s_and_b32 s81, s81, 3
	s_lshl_b32 s81, s81, 15
	s_add_i32 s80, s78, 1
	s_and_b32 s80, s80, 3
	s_lshl_b32 s80, s80, 15
	v_exp_f32_e32 v168, v96
	v_exp_f32_e32 v172, v97
	s_waitcnt lgkmcnt(3)
	v_mfma_f32_32x32x16_bf16 v[48:63], v[10:13], v[124:127], v[48:63]
	ds_read_b128 v[6:9], v14 offset:20992
	v_exp_f32_e32 v174, v98
	v_exp_f32_e32 v176, v99
	s_waitcnt lgkmcnt(3)
	v_mfma_f32_32x32x16_bf16 v[32:47], v[112:115], v[124:127], v[32:47]
	ds_read_b128 v[10:13], v14 offset:21504
	v_exp_f32_e32 v178, v100
	v_exp_f32_e32 v180, v101
	s_waitcnt lgkmcnt(3)
	v_mfma_f32_32x32x16_bf16 v[16:31], v[116:119], v[124:127], v[16:31]
	ds_read_b128 v[96:99], v14 offset:22016
	v_exp_f32_e32 v182, v102
	v_exp_f32_e32 v184, v103
	s_waitcnt lgkmcnt(3)
	v_mfma_f32_32x32x16_bf16 v[64:79], v[2:5], v[128:131], v[64:79]
	ds_read_b128 v[100:103], v14 offset:24576
	v_exp_f32_e32 v186, v104
	v_exp_f32_e32 v188, v105
	s_waitcnt lgkmcnt(3)
	v_mfma_f32_32x32x16_bf16 v[48:63], v[6:9], v[128:131], v[48:63]
	ds_read_b128 v[2:5], v14 offset:25088
	v_exp_f32_e32 v190, v106
	v_exp_f32_e32 v192, v107
	s_waitcnt lgkmcnt(3)
	v_mfma_f32_32x32x16_bf16 v[32:47], v[10:13], v[128:131], v[32:47]
	ds_read_b128 v[6:9], v14 offset:25600
	v_exp_f32_e32 v194, v108
	v_exp_f32_e32 v196, v109
	s_waitcnt lgkmcnt(3)
	v_mfma_f32_32x32x16_bf16 v[16:31], v[96:99], v[128:131], v[16:31]
	ds_read_b128 v[10:13], v14 offset:26112
	v_exp_f32_e32 v198, v110
	v_exp_f32_e32 v200, v111
	s_waitcnt lgkmcnt(3)
	v_mfma_f32_32x32x16_bf16 v[64:79], v[100:103], v[132:135], v[64:79]
	ds_read_b128 v[96:99], v14 offset:28672
	v_exp_f32_e32 v169, v80
	v_exp_f32_e32 v173, v81
	s_waitcnt lgkmcnt(3)
	v_mfma_f32_32x32x16_bf16 v[48:63], v[2:5], v[132:135], v[48:63]
	ds_read_b128 v[100:103], v14 offset:29184
	v_exp_f32_e32 v175, v82
	v_exp_f32_e32 v177, v83
	s_waitcnt lgkmcnt(3)
	v_mfma_f32_32x32x16_bf16 v[32:47], v[6:9], v[132:135], v[32:47]
	ds_read_b128 v[2:5], v14 offset:29696
	v_exp_f32_e32 v179, v84
	v_exp_f32_e32 v181, v85
	s_waitcnt lgkmcnt(3)
	v_mfma_f32_32x32x16_bf16 v[16:31], v[10:13], v[132:135], v[16:31]
	ds_read_b128 v[6:9], v14 offset:30208
	v_exp_f32_e32 v183, v86
	v_exp_f32_e32 v185, v87
	s_waitcnt lgkmcnt(3)
	v_mfma_f32_32x32x16_bf16 v[64:79], v[96:99], v[136:139], v[64:79]
	v_exp_f32_e32 v187, v88
	v_exp_f32_e32 v189, v89
	s_waitcnt lgkmcnt(2)
	v_mfma_f32_32x32x16_bf16 v[48:63], v[100:103], v[136:139], v[48:63]
	v_exp_f32_e32 v191, v90
	v_exp_f32_e32 v193, v91
	s_waitcnt lgkmcnt(1)
	v_mfma_f32_32x32x16_bf16 v[32:47], v[2:5], v[136:139], v[32:47]
	v_exp_f32_e32 v195, v92
	v_exp_f32_e32 v197, v93
	s_waitcnt lgkmcnt(0)
	v_mfma_f32_32x32x16_bf16 v[16:31], v[6:9], v[136:139], v[16:31]
	v_exp_f32_e32 v199, v94
	v_exp_f32_e32 v201, v95
	v_add_f32_e32 v210, v210, v0
	s_branch .Lykb_ynext
